# GEMM main loops: the redundant s_waitcnt lgkmcnt(0) after each segment barrier (the wave already waited in front of the barrier) removed, 4 per iteration
# speedup vs baseline: 1.0024x; 1.0014x over previous
.LBB0_211:
	s_add_i32 s38, s8, 2
	s_add_u32 s39, s6, 0x80
	s_addc_u32 s9, s7, 0
	s_add_i32 s69, 0, 0x10000
	s_cmp_eq_u32 s57, s8
	s_cselect_b32 s9, s1, s9
	s_cselect_b32 s8, s0, s39
	v_add_u32_e32 v0, s69, v156
	s_cselect_b32 s59, s35, s37
	s_cselect_b32 s58, s34, s36
	s_add_i32 s39, 0, 0x14000
	ds_read_b128 v[144:147], v0
	ds_read_b128 v[148:151], v0 offset:1024
	ds_read_b128 v[160:163], v0 offset:2048
	ds_read_b128 v[164:167], v0 offset:3072
	v_add_u32_e32 v0, s39, v156
	ds_read_b128 v[168:171], v0
	ds_read_b128 v[172:175], v0 offset:1024
	ds_read_b128 v[176:179], v0 offset:2048
	ds_read_b128 v[180:183], v0 offset:3072
	v_lshl_add_u64 v[218:219], s[6:7], 0, v[140:141]
	s_add_i32 m0, s50, 0xc000
	ds_read_b128 v[184:187], v158
	ds_read_b128 v[188:191], v158 offset:1024
	ds_read_b128 v[192:195], v158 offset:2048
	ds_read_b128 v[196:199], v158 offset:3072
	ds_read_b128 v[202:205], v158 offset:4096
	ds_read_b128 v[206:209], v158 offset:5120
	ds_read_b128 v[210:213], v158 offset:6144
	ds_read_b128 v[214:217], v158 offset:7168
	global_load_lds_dwordx4 v[218:219], off
	v_lshl_add_u64 v[218:219], s[6:7], 0, v[142:143]
	s_add_i32 m0, s50, 0xe000
	s_nop 0
	global_load_lds_dwordx4 v[218:219], off
	s_waitcnt vmcnt(8)
	s_waitcnt lgkmcnt(0)
	s_barrier
	v_mfma_f32_16x16x32_bf16 v[126:129], v[144:147], v[184:187], v[126:129]
	v_mfma_f32_16x16x32_bf16 v[122:125], v[160:163], v[184:187], v[122:125]
	v_mfma_f32_16x16x32_bf16 v[110:113], v[144:147], v[192:195], v[110:113]
	v_mfma_f32_16x16x32_bf16 v[106:109], v[160:163], v[192:195], v[106:109]
	v_mfma_f32_16x16x32_bf16 v[94:97], v[144:147], v[202:205], v[94:97]
	v_mfma_f32_16x16x32_bf16 v[90:93], v[160:163], v[202:205], v[90:93]
	v_mfma_f32_16x16x32_bf16 v[78:81], v[144:147], v[210:213], v[78:81]
	v_mfma_f32_16x16x32_bf16 v[74:77], v[160:163], v[210:213], v[74:77]
	v_mfma_f32_16x16x32_bf16 v[126:129], v[148:151], v[188:191], v[126:129]
	v_mfma_f32_16x16x32_bf16 v[122:125], v[164:167], v[188:191], v[122:125]
	v_mfma_f32_16x16x32_bf16 v[110:113], v[148:151], v[196:199], v[110:113]
	v_mfma_f32_16x16x32_bf16 v[106:109], v[164:167], v[196:199], v[106:109]
	v_mfma_f32_16x16x32_bf16 v[94:97], v[148:151], v[206:209], v[94:97]
	v_mfma_f32_16x16x32_bf16 v[90:93], v[164:167], v[206:209], v[90:93]
	v_mfma_f32_16x16x32_bf16 v[78:81], v[148:151], v[214:217], v[78:81]
	v_mfma_f32_16x16x32_bf16 v[74:77], v[164:167], v[214:217], v[74:77]
	v_mfma_f32_16x16x32_bf16 v[118:121], v[168:171], v[184:187], v[118:121]
	v_mfma_f32_16x16x32_bf16 v[114:117], v[176:179], v[184:187], v[114:117]
	v_mfma_f32_16x16x32_bf16 v[102:105], v[168:171], v[192:195], v[102:105]
	v_mfma_f32_16x16x32_bf16 v[98:101], v[176:179], v[192:195], v[98:101]
	v_mfma_f32_16x16x32_bf16 v[86:89], v[168:171], v[202:205], v[86:89]
	v_mfma_f32_16x16x32_bf16 v[82:85], v[176:179], v[202:205], v[82:85]
	v_mfma_f32_16x16x32_bf16 v[70:73], v[168:171], v[210:213], v[70:73]
	v_mfma_f32_16x16x32_bf16 v[66:69], v[176:179], v[210:213], v[66:69]
	v_mfma_f32_16x16x32_bf16 v[118:121], v[172:175], v[188:191], v[118:121]
	v_mfma_f32_16x16x32_bf16 v[114:117], v[180:183], v[188:191], v[114:117]
	v_mfma_f32_16x16x32_bf16 v[102:105], v[172:175], v[196:199], v[102:105]
	v_mfma_f32_16x16x32_bf16 v[98:101], v[180:183], v[196:199], v[98:101]
	v_mfma_f32_16x16x32_bf16 v[86:89], v[172:175], v[206:209], v[86:89]
	v_mfma_f32_16x16x32_bf16 v[82:85], v[180:183], v[206:209], v[82:85]
	v_mfma_f32_16x16x32_bf16 v[70:73], v[172:175], v[214:217], v[70:73]
	v_mfma_f32_16x16x32_bf16 v[66:69], v[180:183], v[214:217], v[66:69]
	s_barrier
	s_add_i32 s69, s69, s49
	v_lshl_add_u64 v[218:219], s[58:59], 0, v[136:137]
	s_mov_b32 m0, s69
	ds_read_b128 v[184:187], v158 offset:16384
	ds_read_b128 v[188:191], v158 offset:17408
	ds_read_b128 v[192:195], v158 offset:18432
	ds_read_b128 v[196:199], v158 offset:19456
	ds_read_b128 v[202:205], v158 offset:20480
	ds_read_b128 v[206:209], v158 offset:21504
	ds_read_b128 v[210:213], v158 offset:22528
	ds_read_b128 v[214:217], v158 offset:23552
	global_load_lds_dwordx4 v[218:219], off
	s_add_i32 m0, s69, 0x2000
	v_lshl_add_u64 v[220:221], s[58:59], 0, v[132:133]
	s_add_u32 s58, s58, s47
	s_addc_u32 s59, s59, 0
	s_add_i32 s39, s39, s49
	global_load_lds_dwordx4 v[220:221], off
	v_lshl_add_u64 v[222:223], s[58:59], 0, v[136:137]
	s_mov_b32 m0, s39
	v_lshl_add_u64 v[224:225], s[58:59], 0, v[132:133]
	global_load_lds_dwordx4 v[222:223], off
	s_add_i32 m0, s39, 0x2000
	v_lshl_add_u64 v[226:227], s[8:9], 0, v[134:135]
	global_load_lds_dwordx4 v[224:225], off
	s_mov_b32 m0, s50
	v_lshl_add_u64 v[228:229], s[8:9], 0, v[130:131]
	global_load_lds_dwordx4 v[226:227], off
	s_mov_b32 m0, s51
	s_nop 0
	global_load_lds_dwordx4 v[228:229], off
	s_waitcnt vmcnt(8)
	s_waitcnt lgkmcnt(0)
	s_barrier
	v_mfma_f32_16x16x32_bf16 v[62:65], v[144:147], v[184:187], v[62:65]
	v_mfma_f32_16x16x32_bf16 v[58:61], v[160:163], v[184:187], v[58:61]
	v_mfma_f32_16x16x32_bf16 v[46:49], v[144:147], v[192:195], v[46:49]
	v_mfma_f32_16x16x32_bf16 v[42:45], v[160:163], v[192:195], v[42:45]
	v_mfma_f32_16x16x32_bf16 v[30:33], v[144:147], v[202:205], v[30:33]
	v_mfma_f32_16x16x32_bf16 v[26:29], v[160:163], v[202:205], v[26:29]
	v_mfma_f32_16x16x32_bf16 v[14:17], v[144:147], v[210:213], v[14:17]
	v_mfma_f32_16x16x32_bf16 v[10:13], v[160:163], v[210:213], v[10:13]
	v_mfma_f32_16x16x32_bf16 v[62:65], v[148:151], v[188:191], v[62:65]
	v_mfma_f32_16x16x32_bf16 v[58:61], v[164:167], v[188:191], v[58:61]
	v_mfma_f32_16x16x32_bf16 v[46:49], v[148:151], v[196:199], v[46:49]
	v_mfma_f32_16x16x32_bf16 v[42:45], v[164:167], v[196:199], v[42:45]
	v_mfma_f32_16x16x32_bf16 v[30:33], v[148:151], v[206:209], v[30:33]
	v_mfma_f32_16x16x32_bf16 v[26:29], v[164:167], v[206:209], v[26:29]
	v_mfma_f32_16x16x32_bf16 v[14:17], v[148:151], v[214:217], v[14:17]
	v_mfma_f32_16x16x32_bf16 v[10:13], v[164:167], v[214:217], v[10:13]
	v_mfma_f32_16x16x32_bf16 v[54:57], v[168:171], v[184:187], v[54:57]
	v_mfma_f32_16x16x32_bf16 v[50:53], v[176:179], v[184:187], v[50:53]
	v_mfma_f32_16x16x32_bf16 v[38:41], v[168:171], v[192:195], v[38:41]
	v_mfma_f32_16x16x32_bf16 v[34:37], v[176:179], v[192:195], v[34:37]
	v_mfma_f32_16x16x32_bf16 v[22:25], v[168:171], v[202:205], v[22:25]
	v_mfma_f32_16x16x32_bf16 v[18:21], v[176:179], v[202:205], v[18:21]
	v_mfma_f32_16x16x32_bf16 v[6:9], v[168:171], v[210:213], v[6:9]
	v_mfma_f32_16x16x32_bf16 v[2:5], v[176:179], v[210:213], v[2:5]
	v_mfma_f32_16x16x32_bf16 v[54:57], v[172:175], v[188:191], v[54:57]
	v_mfma_f32_16x16x32_bf16 v[50:53], v[180:183], v[188:191], v[50:53]
	v_mfma_f32_16x16x32_bf16 v[38:41], v[172:175], v[196:199], v[38:41]
	v_mfma_f32_16x16x32_bf16 v[34:37], v[180:183], v[196:199], v[34:37]
	v_mfma_f32_16x16x32_bf16 v[22:25], v[172:175], v[206:209], v[22:25]
	v_mfma_f32_16x16x32_bf16 v[18:21], v[180:183], v[206:209], v[18:21]
	v_mfma_f32_16x16x32_bf16 v[6:9], v[172:175], v[214:217], v[6:9]
	v_mfma_f32_16x16x32_bf16 v[2:5], v[180:183], v[214:217], v[2:5]
	s_barrier
	s_add_i32 s39, 0, 0x18000
	v_add_u32_e32 v0, s39, v156
	s_add_i32 s58, 0, 0x1c000
	ds_read_b128 v[144:147], v0
	ds_read_b128 v[148:151], v0 offset:1024
	ds_read_b128 v[160:163], v0 offset:2048
	ds_read_b128 v[164:167], v0 offset:3072
	v_add_u32_e32 v0, s58, v156
	ds_read_b128 v[168:171], v0
	ds_read_b128 v[172:175], v0 offset:1024
	ds_read_b128 v[176:179], v0 offset:2048
	ds_read_b128 v[180:183], v0 offset:3072
	s_add_u32 s8, s8, s14
	s_addc_u32 s9, s9, 0
	s_mov_b32 m0, s52
	v_lshl_add_u64 v[230:231], s[8:9], 0, v[134:135]
	ds_read_b128 v[184:187], v158 offset:32768
	ds_read_b128 v[188:191], v158 offset:33792
	ds_read_b128 v[192:195], v158 offset:34816
	ds_read_b128 v[196:199], v158 offset:35840
	ds_read_b128 v[202:205], v158 offset:36864
	ds_read_b128 v[206:209], v158 offset:37888
	ds_read_b128 v[210:213], v158 offset:38912
	ds_read_b128 v[214:217], v158 offset:39936
	global_load_lds_dwordx4 v[230:231], off
	v_lshl_add_u64 v[230:231], s[8:9], 0, v[130:131]
	s_mov_b32 m0, s53
	s_nop 0
	global_load_lds_dwordx4 v[230:231], off
	s_waitcnt vmcnt(8)
	s_waitcnt lgkmcnt(0)
	s_barrier
	v_mfma_f32_16x16x32_bf16 v[126:129], v[144:147], v[184:187], v[126:129]
	v_mfma_f32_16x16x32_bf16 v[122:125], v[160:163], v[184:187], v[122:125]
	v_mfma_f32_16x16x32_bf16 v[110:113], v[144:147], v[192:195], v[110:113]
	v_mfma_f32_16x16x32_bf16 v[106:109], v[160:163], v[192:195], v[106:109]
	v_mfma_f32_16x16x32_bf16 v[94:97], v[144:147], v[202:205], v[94:97]
	v_mfma_f32_16x16x32_bf16 v[90:93], v[160:163], v[202:205], v[90:93]
	v_mfma_f32_16x16x32_bf16 v[78:81], v[144:147], v[210:213], v[78:81]
	v_mfma_f32_16x16x32_bf16 v[74:77], v[160:163], v[210:213], v[74:77]
	v_mfma_f32_16x16x32_bf16 v[126:129], v[148:151], v[188:191], v[126:129]
	v_mfma_f32_16x16x32_bf16 v[122:125], v[164:167], v[188:191], v[122:125]
	v_mfma_f32_16x16x32_bf16 v[110:113], v[148:151], v[196:199], v[110:113]
	v_mfma_f32_16x16x32_bf16 v[106:109], v[164:167], v[196:199], v[106:109]
	v_mfma_f32_16x16x32_bf16 v[94:97], v[148:151], v[206:209], v[94:97]
	v_mfma_f32_16x16x32_bf16 v[90:93], v[164:167], v[206:209], v[90:93]
	v_mfma_f32_16x16x32_bf16 v[78:81], v[148:151], v[214:217], v[78:81]
	v_mfma_f32_16x16x32_bf16 v[74:77], v[164:167], v[214:217], v[74:77]
	v_mfma_f32_16x16x32_bf16 v[118:121], v[168:171], v[184:187], v[118:121]
	v_mfma_f32_16x16x32_bf16 v[114:117], v[176:179], v[184:187], v[114:117]
	v_mfma_f32_16x16x32_bf16 v[102:105], v[168:171], v[192:195], v[102:105]
	v_mfma_f32_16x16x32_bf16 v[98:101], v[176:179], v[192:195], v[98:101]
	v_mfma_f32_16x16x32_bf16 v[86:89], v[168:171], v[202:205], v[86:89]
	v_mfma_f32_16x16x32_bf16 v[82:85], v[176:179], v[202:205], v[82:85]
	v_mfma_f32_16x16x32_bf16 v[70:73], v[168:171], v[210:213], v[70:73]
	v_mfma_f32_16x16x32_bf16 v[66:69], v[176:179], v[210:213], v[66:69]
	v_mfma_f32_16x16x32_bf16 v[118:121], v[172:175], v[188:191], v[118:121]
	v_mfma_f32_16x16x32_bf16 v[114:117], v[180:183], v[188:191], v[114:117]
	v_mfma_f32_16x16x32_bf16 v[102:105], v[172:175], v[196:199], v[102:105]
	v_mfma_f32_16x16x32_bf16 v[98:101], v[180:183], v[196:199], v[98:101]
	v_mfma_f32_16x16x32_bf16 v[86:89], v[172:175], v[206:209], v[86:89]
	v_mfma_f32_16x16x32_bf16 v[82:85], v[180:183], v[206:209], v[82:85]
	v_mfma_f32_16x16x32_bf16 v[70:73], v[172:175], v[214:217], v[70:73]
	v_mfma_f32_16x16x32_bf16 v[66:69], v[180:183], v[214:217], v[66:69]
	s_barrier
	s_add_i32 s8, s39, s49
	v_lshl_add_u64 v[218:219], v[218:219], 0, s[16:17]
	s_mov_b32 m0, s8
	ds_read_b128 v[184:187], v158 offset:49152
	ds_read_b128 v[188:191], v158 offset:50176
	ds_read_b128 v[192:195], v158 offset:51200
	ds_read_b128 v[196:199], v158 offset:52224
	ds_read_b128 v[202:205], v158 offset:53248
	ds_read_b128 v[206:209], v158 offset:54272
	ds_read_b128 v[210:213], v158 offset:55296
	ds_read_b128 v[214:217], v158 offset:56320
	global_load_lds_dwordx4 v[218:219], off
	v_lshl_add_u64 v[218:219], v[220:221], 0, s[16:17]
	s_add_i32 m0, s8, 0x2000
	s_add_i32 s8, s58, s49
	global_load_lds_dwordx4 v[218:219], off
	v_lshl_add_u64 v[218:219], v[222:223], 0, s[16:17]
	s_mov_b32 m0, s8
	s_nop 0
	global_load_lds_dwordx4 v[218:219], off
	v_lshl_add_u64 v[218:219], v[224:225], 0, s[16:17]
	s_add_i32 m0, s8, 0x2000
	s_nop 0
	global_load_lds_dwordx4 v[218:219], off
	v_lshl_add_u64 v[218:219], v[226:227], 0, s[16:17]
	s_mov_b32 m0, s54
	s_nop 0
	global_load_lds_dwordx4 v[218:219], off
	v_lshl_add_u64 v[218:219], v[228:229], 0, s[16:17]
	s_mov_b32 m0, s55
	s_nop 0
	global_load_lds_dwordx4 v[218:219], off
	s_waitcnt vmcnt(8)
	s_waitcnt lgkmcnt(0)
	s_barrier
	v_mfma_f32_16x16x32_bf16 v[62:65], v[144:147], v[184:187], v[62:65]
	v_mfma_f32_16x16x32_bf16 v[58:61], v[160:163], v[184:187], v[58:61]
	v_mfma_f32_16x16x32_bf16 v[46:49], v[144:147], v[192:195], v[46:49]
	v_mfma_f32_16x16x32_bf16 v[42:45], v[160:163], v[192:195], v[42:45]
	v_mfma_f32_16x16x32_bf16 v[30:33], v[144:147], v[202:205], v[30:33]
	v_mfma_f32_16x16x32_bf16 v[26:29], v[160:163], v[202:205], v[26:29]
	v_mfma_f32_16x16x32_bf16 v[14:17], v[144:147], v[210:213], v[14:17]
	v_mfma_f32_16x16x32_bf16 v[10:13], v[160:163], v[210:213], v[10:13]
	v_mfma_f32_16x16x32_bf16 v[62:65], v[148:151], v[188:191], v[62:65]
	v_mfma_f32_16x16x32_bf16 v[58:61], v[164:167], v[188:191], v[58:61]
	v_mfma_f32_16x16x32_bf16 v[46:49], v[148:151], v[196:199], v[46:49]
	v_mfma_f32_16x16x32_bf16 v[42:45], v[164:167], v[196:199], v[42:45]
	v_mfma_f32_16x16x32_bf16 v[30:33], v[148:151], v[206:209], v[30:33]
	v_mfma_f32_16x16x32_bf16 v[26:29], v[164:167], v[206:209], v[26:29]
	v_mfma_f32_16x16x32_bf16 v[14:17], v[148:151], v[214:217], v[14:17]
	v_mfma_f32_16x16x32_bf16 v[10:13], v[164:167], v[214:217], v[10:13]
	v_mfma_f32_16x16x32_bf16 v[54:57], v[168:171], v[184:187], v[54:57]
	v_mfma_f32_16x16x32_bf16 v[50:53], v[176:179], v[184:187], v[50:53]
	v_mfma_f32_16x16x32_bf16 v[38:41], v[168:171], v[192:195], v[38:41]
	v_mfma_f32_16x16x32_bf16 v[34:37], v[176:179], v[192:195], v[34:37]
	v_mfma_f32_16x16x32_bf16 v[22:25], v[168:171], v[202:205], v[22:25]
	v_mfma_f32_16x16x32_bf16 v[18:21], v[176:179], v[202:205], v[18:21]
	v_mfma_f32_16x16x32_bf16 v[6:9], v[168:171], v[210:213], v[6:9]
	v_mfma_f32_16x16x32_bf16 v[2:5], v[176:179], v[210:213], v[2:5]
	v_mfma_f32_16x16x32_bf16 v[54:57], v[172:175], v[188:191], v[54:57]
	v_mfma_f32_16x16x32_bf16 v[50:53], v[180:183], v[188:191], v[50:53]
	v_mfma_f32_16x16x32_bf16 v[38:41], v[172:175], v[196:199], v[38:41]
	v_mfma_f32_16x16x32_bf16 v[34:37], v[180:183], v[196:199], v[34:37]
	v_mfma_f32_16x16x32_bf16 v[22:25], v[172:175], v[206:209], v[22:25]
	v_mfma_f32_16x16x32_bf16 v[18:21], v[180:183], v[206:209], v[18:21]
	v_mfma_f32_16x16x32_bf16 v[6:9], v[172:175], v[214:217], v[6:9]
	v_mfma_f32_16x16x32_bf16 v[2:5], v[180:183], v[214:217], v[2:5]
	s_barrier
	s_add_u32 s6, s6, 0x100
	s_addc_u32 s7, s7, 0
	s_add_u32 s36, s36, 0x100
	s_addc_u32 s37, s37, 0
	s_cmp_ge_u32 s38, s56
	s_mov_b32 s8, s38
	s_cbranch_scc0 .LBB0_211
	s_and_b64 vcc, exec, s[28:29]
	s_cbranch_vccnz .LBB0_215
	s_lshl_b32 s8, s3, 8
	s_cmp_lt_i32 s45, 2
	s_mov_b64 s[6:7], -1
	s_cbranch_scc0 .LBB0_216

.LBB0_977:
	s_add_i32 s36, s10, 2
	s_add_u32 s37, s8, 0x80
	s_addc_u32 s11, s9, 0
	s_add_i32 s66, 0, 0x10000
	s_cmp_eq_u32 s55, s10
	s_cselect_b32 s11, s1, s11
	s_cselect_b32 s10, s0, s37
	v_add_u32_e32 v0, s66, v156
	s_cselect_b32 s59, s31, s35
	s_cselect_b32 s58, s30, s34
	s_add_i32 s37, 0, 0x14000
	ds_read_b128 v[144:147], v0
	ds_read_b128 v[148:151], v0 offset:1024
	ds_read_b128 v[160:163], v0 offset:2048
	ds_read_b128 v[164:167], v0 offset:3072
	v_add_u32_e32 v0, s37, v156
	ds_read_b128 v[168:171], v0
	ds_read_b128 v[172:175], v0 offset:1024
	ds_read_b128 v[176:179], v0 offset:2048
	ds_read_b128 v[180:183], v0 offset:3072
	v_lshl_add_u64 v[218:219], s[8:9], 0, v[140:141]
	s_add_i32 m0, s48, 0xc000
	ds_read_b128 v[184:187], v158
	ds_read_b128 v[188:191], v158 offset:1024
	ds_read_b128 v[192:195], v158 offset:2048
	ds_read_b128 v[196:199], v158 offset:3072
	ds_read_b128 v[202:205], v158 offset:4096
	ds_read_b128 v[206:209], v158 offset:5120
	ds_read_b128 v[210:213], v158 offset:6144
	ds_read_b128 v[214:217], v158 offset:7168
	global_load_lds_dwordx4 v[218:219], off
	v_lshl_add_u64 v[218:219], s[8:9], 0, v[142:143]
	s_add_i32 m0, s48, 0xe000
	s_nop 0
	global_load_lds_dwordx4 v[218:219], off
	s_waitcnt vmcnt(8)
	s_waitcnt lgkmcnt(0)
	s_barrier
	v_mfma_f32_16x16x32_bf16 v[126:129], v[144:147], v[184:187], v[126:129]
	v_mfma_f32_16x16x32_bf16 v[122:125], v[160:163], v[184:187], v[122:125]
	v_mfma_f32_16x16x32_bf16 v[110:113], v[144:147], v[192:195], v[110:113]
	v_mfma_f32_16x16x32_bf16 v[106:109], v[160:163], v[192:195], v[106:109]
	v_mfma_f32_16x16x32_bf16 v[94:97], v[144:147], v[202:205], v[94:97]
	v_mfma_f32_16x16x32_bf16 v[90:93], v[160:163], v[202:205], v[90:93]
	v_mfma_f32_16x16x32_bf16 v[78:81], v[144:147], v[210:213], v[78:81]
	v_mfma_f32_16x16x32_bf16 v[74:77], v[160:163], v[210:213], v[74:77]
	v_mfma_f32_16x16x32_bf16 v[126:129], v[148:151], v[188:191], v[126:129]
	v_mfma_f32_16x16x32_bf16 v[122:125], v[164:167], v[188:191], v[122:125]
	v_mfma_f32_16x16x32_bf16 v[110:113], v[148:151], v[196:199], v[110:113]
	v_mfma_f32_16x16x32_bf16 v[106:109], v[164:167], v[196:199], v[106:109]
	v_mfma_f32_16x16x32_bf16 v[94:97], v[148:151], v[206:209], v[94:97]
	v_mfma_f32_16x16x32_bf16 v[90:93], v[164:167], v[206:209], v[90:93]
	v_mfma_f32_16x16x32_bf16 v[78:81], v[148:151], v[214:217], v[78:81]
	v_mfma_f32_16x16x32_bf16 v[74:77], v[164:167], v[214:217], v[74:77]
	v_mfma_f32_16x16x32_bf16 v[118:121], v[168:171], v[184:187], v[118:121]
	v_mfma_f32_16x16x32_bf16 v[114:117], v[176:179], v[184:187], v[114:117]
	v_mfma_f32_16x16x32_bf16 v[102:105], v[168:171], v[192:195], v[102:105]
	v_mfma_f32_16x16x32_bf16 v[98:101], v[176:179], v[192:195], v[98:101]
	v_mfma_f32_16x16x32_bf16 v[86:89], v[168:171], v[202:205], v[86:89]
	v_mfma_f32_16x16x32_bf16 v[82:85], v[176:179], v[202:205], v[82:85]
	v_mfma_f32_16x16x32_bf16 v[70:73], v[168:171], v[210:213], v[70:73]
	v_mfma_f32_16x16x32_bf16 v[66:69], v[176:179], v[210:213], v[66:69]
	v_mfma_f32_16x16x32_bf16 v[118:121], v[172:175], v[188:191], v[118:121]
	v_mfma_f32_16x16x32_bf16 v[114:117], v[180:183], v[188:191], v[114:117]
	v_mfma_f32_16x16x32_bf16 v[102:105], v[172:175], v[196:199], v[102:105]
	v_mfma_f32_16x16x32_bf16 v[98:101], v[180:183], v[196:199], v[98:101]
	v_mfma_f32_16x16x32_bf16 v[86:89], v[172:175], v[206:209], v[86:89]
	v_mfma_f32_16x16x32_bf16 v[82:85], v[180:183], v[206:209], v[82:85]
	v_mfma_f32_16x16x32_bf16 v[70:73], v[172:175], v[214:217], v[70:73]
	v_mfma_f32_16x16x32_bf16 v[66:69], v[180:183], v[214:217], v[66:69]
	s_barrier
	s_add_i32 s66, s66, s47
	v_lshl_add_u64 v[218:219], s[58:59], 0, v[136:137]
	s_mov_b32 m0, s66
	ds_read_b128 v[184:187], v158 offset:16384
	ds_read_b128 v[188:191], v158 offset:17408
	ds_read_b128 v[192:195], v158 offset:18432
	ds_read_b128 v[196:199], v158 offset:19456
	ds_read_b128 v[202:205], v158 offset:20480
	ds_read_b128 v[206:209], v158 offset:21504
	ds_read_b128 v[210:213], v158 offset:22528
	ds_read_b128 v[214:217], v158 offset:23552
	global_load_lds_dwordx4 v[218:219], off
	s_add_i32 m0, s66, 0x2000
	v_lshl_add_u64 v[220:221], s[58:59], 0, v[132:133]
	s_add_u32 s58, s58, s45
	s_addc_u32 s59, s59, 0
	s_add_i32 s37, s37, s47
	global_load_lds_dwordx4 v[220:221], off
	v_lshl_add_u64 v[222:223], s[58:59], 0, v[136:137]
	s_mov_b32 m0, s37
	v_lshl_add_u64 v[224:225], s[58:59], 0, v[132:133]
	global_load_lds_dwordx4 v[222:223], off
	s_add_i32 m0, s37, 0x2000
	v_lshl_add_u64 v[226:227], s[10:11], 0, v[134:135]
	global_load_lds_dwordx4 v[224:225], off
	s_mov_b32 m0, s48
	v_lshl_add_u64 v[228:229], s[10:11], 0, v[130:131]
	global_load_lds_dwordx4 v[226:227], off
	s_mov_b32 m0, s49
	s_nop 0
	global_load_lds_dwordx4 v[228:229], off
	s_waitcnt vmcnt(8)
	s_waitcnt lgkmcnt(0)
	s_barrier
	v_mfma_f32_16x16x32_bf16 v[62:65], v[144:147], v[184:187], v[62:65]
	v_mfma_f32_16x16x32_bf16 v[58:61], v[160:163], v[184:187], v[58:61]
	v_mfma_f32_16x16x32_bf16 v[46:49], v[144:147], v[192:195], v[46:49]
	v_mfma_f32_16x16x32_bf16 v[42:45], v[160:163], v[192:195], v[42:45]
	v_mfma_f32_16x16x32_bf16 v[30:33], v[144:147], v[202:205], v[30:33]
	v_mfma_f32_16x16x32_bf16 v[26:29], v[160:163], v[202:205], v[26:29]
	v_mfma_f32_16x16x32_bf16 v[14:17], v[144:147], v[210:213], v[14:17]
	v_mfma_f32_16x16x32_bf16 v[10:13], v[160:163], v[210:213], v[10:13]
	v_mfma_f32_16x16x32_bf16 v[62:65], v[148:151], v[188:191], v[62:65]
	v_mfma_f32_16x16x32_bf16 v[58:61], v[164:167], v[188:191], v[58:61]
	v_mfma_f32_16x16x32_bf16 v[46:49], v[148:151], v[196:199], v[46:49]
	v_mfma_f32_16x16x32_bf16 v[42:45], v[164:167], v[196:199], v[42:45]
	v_mfma_f32_16x16x32_bf16 v[30:33], v[148:151], v[206:209], v[30:33]
	v_mfma_f32_16x16x32_bf16 v[26:29], v[164:167], v[206:209], v[26:29]
	v_mfma_f32_16x16x32_bf16 v[14:17], v[148:151], v[214:217], v[14:17]
	v_mfma_f32_16x16x32_bf16 v[10:13], v[164:167], v[214:217], v[10:13]
	v_mfma_f32_16x16x32_bf16 v[54:57], v[168:171], v[184:187], v[54:57]
	v_mfma_f32_16x16x32_bf16 v[50:53], v[176:179], v[184:187], v[50:53]
	v_mfma_f32_16x16x32_bf16 v[38:41], v[168:171], v[192:195], v[38:41]
	v_mfma_f32_16x16x32_bf16 v[34:37], v[176:179], v[192:195], v[34:37]
	v_mfma_f32_16x16x32_bf16 v[22:25], v[168:171], v[202:205], v[22:25]
	v_mfma_f32_16x16x32_bf16 v[18:21], v[176:179], v[202:205], v[18:21]
	v_mfma_f32_16x16x32_bf16 v[6:9], v[168:171], v[210:213], v[6:9]
	v_mfma_f32_16x16x32_bf16 v[2:5], v[176:179], v[210:213], v[2:5]
	v_mfma_f32_16x16x32_bf16 v[54:57], v[172:175], v[188:191], v[54:57]
	v_mfma_f32_16x16x32_bf16 v[50:53], v[180:183], v[188:191], v[50:53]
	v_mfma_f32_16x16x32_bf16 v[38:41], v[172:175], v[196:199], v[38:41]
	v_mfma_f32_16x16x32_bf16 v[34:37], v[180:183], v[196:199], v[34:37]
	v_mfma_f32_16x16x32_bf16 v[22:25], v[172:175], v[206:209], v[22:25]
	v_mfma_f32_16x16x32_bf16 v[18:21], v[180:183], v[206:209], v[18:21]
	v_mfma_f32_16x16x32_bf16 v[6:9], v[172:175], v[214:217], v[6:9]
	v_mfma_f32_16x16x32_bf16 v[2:5], v[180:183], v[214:217], v[2:5]
	s_barrier
	s_add_i32 s37, 0, 0x18000
	v_add_u32_e32 v0, s37, v156
	s_add_i32 s58, 0, 0x1c000
	ds_read_b128 v[144:147], v0
	ds_read_b128 v[148:151], v0 offset:1024
	ds_read_b128 v[160:163], v0 offset:2048
	ds_read_b128 v[164:167], v0 offset:3072
	v_add_u32_e32 v0, s58, v156
	ds_read_b128 v[168:171], v0
	ds_read_b128 v[172:175], v0 offset:1024
	ds_read_b128 v[176:179], v0 offset:2048
	ds_read_b128 v[180:183], v0 offset:3072
	s_add_u32 s10, s10, s12
	s_addc_u32 s11, s11, 0
	s_mov_b32 m0, s50
	v_lshl_add_u64 v[230:231], s[10:11], 0, v[134:135]
	ds_read_b128 v[184:187], v158 offset:32768
	ds_read_b128 v[188:191], v158 offset:33792
	ds_read_b128 v[192:195], v158 offset:34816
	ds_read_b128 v[196:199], v158 offset:35840
	ds_read_b128 v[202:205], v158 offset:36864
	ds_read_b128 v[206:209], v158 offset:37888
	ds_read_b128 v[210:213], v158 offset:38912
	ds_read_b128 v[214:217], v158 offset:39936
	global_load_lds_dwordx4 v[230:231], off
	v_lshl_add_u64 v[230:231], s[10:11], 0, v[130:131]
	s_mov_b32 m0, s51
	s_nop 0
	global_load_lds_dwordx4 v[230:231], off
	s_waitcnt vmcnt(8)
	s_waitcnt lgkmcnt(0)
	s_barrier
	v_mfma_f32_16x16x32_bf16 v[126:129], v[144:147], v[184:187], v[126:129]
	v_mfma_f32_16x16x32_bf16 v[122:125], v[160:163], v[184:187], v[122:125]
	v_mfma_f32_16x16x32_bf16 v[110:113], v[144:147], v[192:195], v[110:113]
	v_mfma_f32_16x16x32_bf16 v[106:109], v[160:163], v[192:195], v[106:109]
	v_mfma_f32_16x16x32_bf16 v[94:97], v[144:147], v[202:205], v[94:97]
	v_mfma_f32_16x16x32_bf16 v[90:93], v[160:163], v[202:205], v[90:93]
	v_mfma_f32_16x16x32_bf16 v[78:81], v[144:147], v[210:213], v[78:81]
	v_mfma_f32_16x16x32_bf16 v[74:77], v[160:163], v[210:213], v[74:77]
	v_mfma_f32_16x16x32_bf16 v[126:129], v[148:151], v[188:191], v[126:129]
	v_mfma_f32_16x16x32_bf16 v[122:125], v[164:167], v[188:191], v[122:125]
	v_mfma_f32_16x16x32_bf16 v[110:113], v[148:151], v[196:199], v[110:113]
	v_mfma_f32_16x16x32_bf16 v[106:109], v[164:167], v[196:199], v[106:109]
	v_mfma_f32_16x16x32_bf16 v[94:97], v[148:151], v[206:209], v[94:97]
	v_mfma_f32_16x16x32_bf16 v[90:93], v[164:167], v[206:209], v[90:93]
	v_mfma_f32_16x16x32_bf16 v[78:81], v[148:151], v[214:217], v[78:81]
	v_mfma_f32_16x16x32_bf16 v[74:77], v[164:167], v[214:217], v[74:77]
	v_mfma_f32_16x16x32_bf16 v[118:121], v[168:171], v[184:187], v[118:121]
	v_mfma_f32_16x16x32_bf16 v[114:117], v[176:179], v[184:187], v[114:117]
	v_mfma_f32_16x16x32_bf16 v[102:105], v[168:171], v[192:195], v[102:105]
	v_mfma_f32_16x16x32_bf16 v[98:101], v[176:179], v[192:195], v[98:101]
	v_mfma_f32_16x16x32_bf16 v[86:89], v[168:171], v[202:205], v[86:89]
	v_mfma_f32_16x16x32_bf16 v[82:85], v[176:179], v[202:205], v[82:85]
	v_mfma_f32_16x16x32_bf16 v[70:73], v[168:171], v[210:213], v[70:73]
	v_mfma_f32_16x16x32_bf16 v[66:69], v[176:179], v[210:213], v[66:69]
	v_mfma_f32_16x16x32_bf16 v[118:121], v[172:175], v[188:191], v[118:121]
	v_mfma_f32_16x16x32_bf16 v[114:117], v[180:183], v[188:191], v[114:117]
	v_mfma_f32_16x16x32_bf16 v[102:105], v[172:175], v[196:199], v[102:105]
	v_mfma_f32_16x16x32_bf16 v[98:101], v[180:183], v[196:199], v[98:101]
	v_mfma_f32_16x16x32_bf16 v[86:89], v[172:175], v[206:209], v[86:89]
	v_mfma_f32_16x16x32_bf16 v[82:85], v[180:183], v[206:209], v[82:85]
	v_mfma_f32_16x16x32_bf16 v[70:73], v[172:175], v[214:217], v[70:73]
	v_mfma_f32_16x16x32_bf16 v[66:69], v[180:183], v[214:217], v[66:69]
	s_barrier
	s_add_i32 s10, s37, s47
	v_lshl_add_u64 v[218:219], v[218:219], 0, s[14:15]
	s_mov_b32 m0, s10
	ds_read_b128 v[184:187], v158 offset:49152
	ds_read_b128 v[188:191], v158 offset:50176
	ds_read_b128 v[192:195], v158 offset:51200
	ds_read_b128 v[196:199], v158 offset:52224
	ds_read_b128 v[202:205], v158 offset:53248
	ds_read_b128 v[206:209], v158 offset:54272
	ds_read_b128 v[210:213], v158 offset:55296
	ds_read_b128 v[214:217], v158 offset:56320
	global_load_lds_dwordx4 v[218:219], off
	v_lshl_add_u64 v[218:219], v[220:221], 0, s[14:15]
	s_add_i32 m0, s10, 0x2000
	s_add_i32 s10, s58, s47
	global_load_lds_dwordx4 v[218:219], off
	v_lshl_add_u64 v[218:219], v[222:223], 0, s[14:15]
	s_mov_b32 m0, s10
	s_nop 0
	global_load_lds_dwordx4 v[218:219], off
	v_lshl_add_u64 v[218:219], v[224:225], 0, s[14:15]
	s_add_i32 m0, s10, 0x2000
	s_nop 0
	global_load_lds_dwordx4 v[218:219], off
	v_lshl_add_u64 v[218:219], v[226:227], 0, s[14:15]
	s_mov_b32 m0, s53
	s_nop 0
	global_load_lds_dwordx4 v[218:219], off
	v_lshl_add_u64 v[218:219], v[228:229], 0, s[14:15]
	s_mov_b32 m0, s54
	s_nop 0
	global_load_lds_dwordx4 v[218:219], off
	s_waitcnt vmcnt(8)
	s_waitcnt lgkmcnt(0)
	s_barrier
	v_mfma_f32_16x16x32_bf16 v[62:65], v[144:147], v[184:187], v[62:65]
	v_mfma_f32_16x16x32_bf16 v[58:61], v[160:163], v[184:187], v[58:61]
	v_mfma_f32_16x16x32_bf16 v[46:49], v[144:147], v[192:195], v[46:49]
	v_mfma_f32_16x16x32_bf16 v[42:45], v[160:163], v[192:195], v[42:45]
	v_mfma_f32_16x16x32_bf16 v[30:33], v[144:147], v[202:205], v[30:33]
	v_mfma_f32_16x16x32_bf16 v[26:29], v[160:163], v[202:205], v[26:29]
	v_mfma_f32_16x16x32_bf16 v[14:17], v[144:147], v[210:213], v[14:17]
	v_mfma_f32_16x16x32_bf16 v[10:13], v[160:163], v[210:213], v[10:13]
	v_mfma_f32_16x16x32_bf16 v[62:65], v[148:151], v[188:191], v[62:65]
	v_mfma_f32_16x16x32_bf16 v[58:61], v[164:167], v[188:191], v[58:61]
	v_mfma_f32_16x16x32_bf16 v[46:49], v[148:151], v[196:199], v[46:49]
	v_mfma_f32_16x16x32_bf16 v[42:45], v[164:167], v[196:199], v[42:45]
	v_mfma_f32_16x16x32_bf16 v[30:33], v[148:151], v[206:209], v[30:33]
	v_mfma_f32_16x16x32_bf16 v[26:29], v[164:167], v[206:209], v[26:29]
	v_mfma_f32_16x16x32_bf16 v[14:17], v[148:151], v[214:217], v[14:17]
	v_mfma_f32_16x16x32_bf16 v[10:13], v[164:167], v[214:217], v[10:13]
	v_mfma_f32_16x16x32_bf16 v[54:57], v[168:171], v[184:187], v[54:57]
	v_mfma_f32_16x16x32_bf16 v[50:53], v[176:179], v[184:187], v[50:53]
	v_mfma_f32_16x16x32_bf16 v[38:41], v[168:171], v[192:195], v[38:41]
	v_mfma_f32_16x16x32_bf16 v[34:37], v[176:179], v[192:195], v[34:37]
	v_mfma_f32_16x16x32_bf16 v[22:25], v[168:171], v[202:205], v[22:25]
	v_mfma_f32_16x16x32_bf16 v[18:21], v[176:179], v[202:205], v[18:21]
	v_mfma_f32_16x16x32_bf16 v[6:9], v[168:171], v[210:213], v[6:9]
	v_mfma_f32_16x16x32_bf16 v[2:5], v[176:179], v[210:213], v[2:5]
	v_mfma_f32_16x16x32_bf16 v[54:57], v[172:175], v[188:191], v[54:57]
	v_mfma_f32_16x16x32_bf16 v[50:53], v[180:183], v[188:191], v[50:53]
	v_mfma_f32_16x16x32_bf16 v[38:41], v[172:175], v[196:199], v[38:41]
	v_mfma_f32_16x16x32_bf16 v[34:37], v[180:183], v[196:199], v[34:37]
	v_mfma_f32_16x16x32_bf16 v[22:25], v[172:175], v[206:209], v[22:25]
	v_mfma_f32_16x16x32_bf16 v[18:21], v[180:183], v[206:209], v[18:21]
	v_mfma_f32_16x16x32_bf16 v[6:9], v[172:175], v[214:217], v[6:9]
	v_mfma_f32_16x16x32_bf16 v[2:5], v[180:183], v[214:217], v[2:5]
	s_barrier
	s_add_u32 s8, s8, 0x100
	s_addc_u32 s9, s9, 0
	s_add_u32 s34, s34, 0x100
	s_addc_u32 s35, s35, 0
	s_cmp_ge_u32 s36, s52
	s_mov_b32 s10, s36
	s_cbranch_scc0 .LBB0_977

.Lg2_first:
	s_mov_b32 s32, 0
	s_add_i32 s36, s10, 2
	s_add_u32 s37, s8, 0x80
	s_addc_u32 s11, s9, 0
	s_add_i32 s66, 0, 0x10000
	s_cmp_eq_u32 s55, s10
	s_cselect_b32 s11, s1, s11
	s_cselect_b32 s10, s0, s37
	v_add_u32_e32 v0, s66, v156
	s_cselect_b32 s59, s31, s35
	s_cselect_b32 s58, s30, s34
	s_add_i32 s37, 0, 0x14000
	ds_read_b128 v[144:147], v0
	ds_read_b128 v[148:151], v0 offset:1024
	ds_read_b128 v[160:163], v0 offset:2048
	ds_read_b128 v[164:167], v0 offset:3072
	v_add_u32_e32 v0, s37, v156
	ds_read_b128 v[168:171], v0
	ds_read_b128 v[172:175], v0 offset:1024
	ds_read_b128 v[176:179], v0 offset:2048
	ds_read_b128 v[180:183], v0 offset:3072
	v_lshl_add_u64 v[218:219], s[8:9], 0, v[140:141]
	s_add_i32 m0, s48, 0xc000
	ds_read_b128 v[184:187], v158
	ds_read_b128 v[188:191], v158 offset:1024
	ds_read_b128 v[192:195], v158 offset:2048
	ds_read_b128 v[196:199], v158 offset:3072
	ds_read_b128 v[202:205], v158 offset:4096
	ds_read_b128 v[206:209], v158 offset:5120
	ds_read_b128 v[210:213], v158 offset:6144
	ds_read_b128 v[214:217], v158 offset:7168
	global_load_lds_dwordx4 v[218:219], off
	v_lshl_add_u64 v[218:219], s[8:9], 0, v[142:143]
	s_add_i32 m0, s48, 0xe000
	s_nop 0
	global_load_lds_dwordx4 v[218:219], off
	s_waitcnt lgkmcnt(0)
	s_barrier
	v_mfma_f32_16x16x32_bf16 v[126:129], v[144:147], v[184:187], 0
	v_mfma_f32_16x16x32_bf16 v[122:125], v[160:163], v[184:187], 0
	v_mfma_f32_16x16x32_bf16 v[110:113], v[144:147], v[192:195], 0
	v_mfma_f32_16x16x32_bf16 v[106:109], v[160:163], v[192:195], 0
	v_mfma_f32_16x16x32_bf16 v[94:97], v[144:147], v[202:205], 0
	v_mfma_f32_16x16x32_bf16 v[90:93], v[160:163], v[202:205], 0
	v_mfma_f32_16x16x32_bf16 v[78:81], v[144:147], v[210:213], 0
	v_mfma_f32_16x16x32_bf16 v[74:77], v[160:163], v[210:213], 0
	v_mfma_f32_16x16x32_bf16 v[126:129], v[148:151], v[188:191], v[126:129]
	v_mfma_f32_16x16x32_bf16 v[122:125], v[164:167], v[188:191], v[122:125]
	v_mfma_f32_16x16x32_bf16 v[110:113], v[148:151], v[196:199], v[110:113]
	v_mfma_f32_16x16x32_bf16 v[106:109], v[164:167], v[196:199], v[106:109]
	v_mfma_f32_16x16x32_bf16 v[94:97], v[148:151], v[206:209], v[94:97]
	v_mfma_f32_16x16x32_bf16 v[90:93], v[164:167], v[206:209], v[90:93]
	v_mfma_f32_16x16x32_bf16 v[78:81], v[148:151], v[214:217], v[78:81]
	v_mfma_f32_16x16x32_bf16 v[74:77], v[164:167], v[214:217], v[74:77]
	v_mfma_f32_16x16x32_bf16 v[118:121], v[168:171], v[184:187], 0
	v_mfma_f32_16x16x32_bf16 v[114:117], v[176:179], v[184:187], 0
	v_mfma_f32_16x16x32_bf16 v[102:105], v[168:171], v[192:195], 0
	v_mfma_f32_16x16x32_bf16 v[98:101], v[176:179], v[192:195], 0
	v_mfma_f32_16x16x32_bf16 v[86:89], v[168:171], v[202:205], 0
	v_mfma_f32_16x16x32_bf16 v[82:85], v[176:179], v[202:205], 0
	v_mfma_f32_16x16x32_bf16 v[70:73], v[168:171], v[210:213], 0
	v_mfma_f32_16x16x32_bf16 v[66:69], v[176:179], v[210:213], 0
	v_mfma_f32_16x16x32_bf16 v[118:121], v[172:175], v[188:191], v[118:121]
	v_mfma_f32_16x16x32_bf16 v[114:117], v[180:183], v[188:191], v[114:117]
	v_mfma_f32_16x16x32_bf16 v[102:105], v[172:175], v[196:199], v[102:105]
	v_mfma_f32_16x16x32_bf16 v[98:101], v[180:183], v[196:199], v[98:101]
	v_mfma_f32_16x16x32_bf16 v[86:89], v[172:175], v[206:209], v[86:89]
	v_mfma_f32_16x16x32_bf16 v[82:85], v[180:183], v[206:209], v[82:85]
	v_mfma_f32_16x16x32_bf16 v[70:73], v[172:175], v[214:217], v[70:73]
	v_mfma_f32_16x16x32_bf16 v[66:69], v[180:183], v[214:217], v[66:69]
	s_barrier
	s_add_i32 s66, s66, s47
	v_lshl_add_u64 v[218:219], s[58:59], 0, v[136:137]
	s_mov_b32 m0, s66
	ds_read_b128 v[184:187], v158 offset:16384
	ds_read_b128 v[188:191], v158 offset:17408
	ds_read_b128 v[192:195], v158 offset:18432
	ds_read_b128 v[196:199], v158 offset:19456
	ds_read_b128 v[202:205], v158 offset:20480
	ds_read_b128 v[206:209], v158 offset:21504
	ds_read_b128 v[210:213], v158 offset:22528
	ds_read_b128 v[214:217], v158 offset:23552
	global_load_lds_dwordx4 v[218:219], off
	s_add_i32 m0, s66, 0x2000
	v_lshl_add_u64 v[220:221], s[58:59], 0, v[132:133]
	s_add_u32 s58, s58, s45
	s_addc_u32 s59, s59, 0
	s_add_i32 s37, s37, s47
	global_load_lds_dwordx4 v[220:221], off
	v_lshl_add_u64 v[222:223], s[58:59], 0, v[136:137]
	s_mov_b32 m0, s37
	v_lshl_add_u64 v[224:225], s[58:59], 0, v[132:133]
	global_load_lds_dwordx4 v[222:223], off
	s_add_i32 m0, s37, 0x2000
	v_lshl_add_u64 v[226:227], s[10:11], 0, v[134:135]
	global_load_lds_dwordx4 v[224:225], off
	s_mov_b32 m0, s48
	v_lshl_add_u64 v[228:229], s[10:11], 0, v[130:131]
	global_load_lds_dwordx4 v[226:227], off
	s_mov_b32 m0, s49
	s_nop 0
	global_load_lds_dwordx4 v[228:229], off
	s_waitcnt lgkmcnt(0)
	s_barrier
	v_mfma_f32_16x16x32_bf16 v[62:65], v[144:147], v[184:187], 0
	v_mfma_f32_16x16x32_bf16 v[58:61], v[160:163], v[184:187], 0
	v_mfma_f32_16x16x32_bf16 v[46:49], v[144:147], v[192:195], 0
	v_mfma_f32_16x16x32_bf16 v[42:45], v[160:163], v[192:195], 0
	v_mfma_f32_16x16x32_bf16 v[30:33], v[144:147], v[202:205], 0
	v_mfma_f32_16x16x32_bf16 v[26:29], v[160:163], v[202:205], 0
	v_mfma_f32_16x16x32_bf16 v[14:17], v[144:147], v[210:213], 0
	v_mfma_f32_16x16x32_bf16 v[10:13], v[160:163], v[210:213], 0
	v_mfma_f32_16x16x32_bf16 v[62:65], v[148:151], v[188:191], v[62:65]
	v_mfma_f32_16x16x32_bf16 v[58:61], v[164:167], v[188:191], v[58:61]
	v_mfma_f32_16x16x32_bf16 v[46:49], v[148:151], v[196:199], v[46:49]
	v_mfma_f32_16x16x32_bf16 v[42:45], v[164:167], v[196:199], v[42:45]
	v_mfma_f32_16x16x32_bf16 v[30:33], v[148:151], v[206:209], v[30:33]
	v_mfma_f32_16x16x32_bf16 v[26:29], v[164:167], v[206:209], v[26:29]
	v_mfma_f32_16x16x32_bf16 v[14:17], v[148:151], v[214:217], v[14:17]
	v_mfma_f32_16x16x32_bf16 v[10:13], v[164:167], v[214:217], v[10:13]
	v_mfma_f32_16x16x32_bf16 v[54:57], v[168:171], v[184:187], 0
	v_mfma_f32_16x16x32_bf16 v[50:53], v[176:179], v[184:187], 0
	v_mfma_f32_16x16x32_bf16 v[38:41], v[168:171], v[192:195], 0
	v_mfma_f32_16x16x32_bf16 v[34:37], v[176:179], v[192:195], 0
	v_mfma_f32_16x16x32_bf16 v[22:25], v[168:171], v[202:205], 0
	v_mfma_f32_16x16x32_bf16 v[18:21], v[176:179], v[202:205], 0
	v_mfma_f32_16x16x32_bf16 v[6:9], v[168:171], v[210:213], 0
	v_mfma_f32_16x16x32_bf16 v[2:5], v[176:179], v[210:213], 0
	v_mfma_f32_16x16x32_bf16 v[54:57], v[172:175], v[188:191], v[54:57]
	v_mfma_f32_16x16x32_bf16 v[50:53], v[180:183], v[188:191], v[50:53]
	v_mfma_f32_16x16x32_bf16 v[38:41], v[172:175], v[196:199], v[38:41]
	v_mfma_f32_16x16x32_bf16 v[34:37], v[180:183], v[196:199], v[34:37]
	v_mfma_f32_16x16x32_bf16 v[22:25], v[172:175], v[206:209], v[22:25]
	v_mfma_f32_16x16x32_bf16 v[18:21], v[180:183], v[206:209], v[18:21]
	v_mfma_f32_16x16x32_bf16 v[6:9], v[172:175], v[214:217], v[6:9]
	v_mfma_f32_16x16x32_bf16 v[2:5], v[180:183], v[214:217], v[2:5]
	s_barrier
	s_add_i32 s37, 0, 0x18000
	v_add_u32_e32 v0, s37, v156
	s_add_i32 s58, 0, 0x1c000
	ds_read_b128 v[144:147], v0
	ds_read_b128 v[148:151], v0 offset:1024
	ds_read_b128 v[160:163], v0 offset:2048
	ds_read_b128 v[164:167], v0 offset:3072
	v_add_u32_e32 v0, s58, v156
	ds_read_b128 v[168:171], v0
	ds_read_b128 v[172:175], v0 offset:1024
	ds_read_b128 v[176:179], v0 offset:2048
	ds_read_b128 v[180:183], v0 offset:3072
	s_add_u32 s10, s10, s12
	s_addc_u32 s11, s11, 0
	s_mov_b32 m0, s50
	v_lshl_add_u64 v[230:231], s[10:11], 0, v[134:135]
	ds_read_b128 v[184:187], v158 offset:32768
	ds_read_b128 v[188:191], v158 offset:33792
	ds_read_b128 v[192:195], v158 offset:34816
	ds_read_b128 v[196:199], v158 offset:35840
	ds_read_b128 v[202:205], v158 offset:36864
	ds_read_b128 v[206:209], v158 offset:37888
	ds_read_b128 v[210:213], v158 offset:38912
	ds_read_b128 v[214:217], v158 offset:39936
	global_load_lds_dwordx4 v[230:231], off
	v_lshl_add_u64 v[230:231], s[10:11], 0, v[130:131]
	s_mov_b32 m0, s51
	s_nop 0
	global_load_lds_dwordx4 v[230:231], off
	s_waitcnt vmcnt(8)
	s_waitcnt lgkmcnt(0)
	s_barrier
	v_mfma_f32_16x16x32_bf16 v[126:129], v[144:147], v[184:187], v[126:129]
	v_mfma_f32_16x16x32_bf16 v[122:125], v[160:163], v[184:187], v[122:125]
	v_mfma_f32_16x16x32_bf16 v[110:113], v[144:147], v[192:195], v[110:113]
	v_mfma_f32_16x16x32_bf16 v[106:109], v[160:163], v[192:195], v[106:109]
	v_mfma_f32_16x16x32_bf16 v[94:97], v[144:147], v[202:205], v[94:97]
	v_mfma_f32_16x16x32_bf16 v[90:93], v[160:163], v[202:205], v[90:93]
	v_mfma_f32_16x16x32_bf16 v[78:81], v[144:147], v[210:213], v[78:81]
	v_mfma_f32_16x16x32_bf16 v[74:77], v[160:163], v[210:213], v[74:77]
	v_mfma_f32_16x16x32_bf16 v[126:129], v[148:151], v[188:191], v[126:129]
	v_mfma_f32_16x16x32_bf16 v[122:125], v[164:167], v[188:191], v[122:125]
	v_mfma_f32_16x16x32_bf16 v[110:113], v[148:151], v[196:199], v[110:113]
	v_mfma_f32_16x16x32_bf16 v[106:109], v[164:167], v[196:199], v[106:109]
	v_mfma_f32_16x16x32_bf16 v[94:97], v[148:151], v[206:209], v[94:97]
	v_mfma_f32_16x16x32_bf16 v[90:93], v[164:167], v[206:209], v[90:93]
	v_mfma_f32_16x16x32_bf16 v[78:81], v[148:151], v[214:217], v[78:81]
	v_mfma_f32_16x16x32_bf16 v[74:77], v[164:167], v[214:217], v[74:77]
	v_mfma_f32_16x16x32_bf16 v[118:121], v[168:171], v[184:187], v[118:121]
	v_mfma_f32_16x16x32_bf16 v[114:117], v[176:179], v[184:187], v[114:117]
	v_mfma_f32_16x16x32_bf16 v[102:105], v[168:171], v[192:195], v[102:105]
	v_mfma_f32_16x16x32_bf16 v[98:101], v[176:179], v[192:195], v[98:101]
	v_mfma_f32_16x16x32_bf16 v[86:89], v[168:171], v[202:205], v[86:89]
	v_mfma_f32_16x16x32_bf16 v[82:85], v[176:179], v[202:205], v[82:85]
	v_mfma_f32_16x16x32_bf16 v[70:73], v[168:171], v[210:213], v[70:73]
	v_mfma_f32_16x16x32_bf16 v[66:69], v[176:179], v[210:213], v[66:69]
	v_mfma_f32_16x16x32_bf16 v[118:121], v[172:175], v[188:191], v[118:121]
	v_mfma_f32_16x16x32_bf16 v[114:117], v[180:183], v[188:191], v[114:117]
	v_mfma_f32_16x16x32_bf16 v[102:105], v[172:175], v[196:199], v[102:105]
	v_mfma_f32_16x16x32_bf16 v[98:101], v[180:183], v[196:199], v[98:101]
	v_mfma_f32_16x16x32_bf16 v[86:89], v[172:175], v[206:209], v[86:89]
	v_mfma_f32_16x16x32_bf16 v[82:85], v[180:183], v[206:209], v[82:85]
	v_mfma_f32_16x16x32_bf16 v[70:73], v[172:175], v[214:217], v[70:73]
	v_mfma_f32_16x16x32_bf16 v[66:69], v[180:183], v[214:217], v[66:69]
	s_barrier
	s_add_i32 s10, s37, s47
	v_lshl_add_u64 v[218:219], v[218:219], 0, s[14:15]
	s_mov_b32 m0, s10
	ds_read_b128 v[184:187], v158 offset:49152
	ds_read_b128 v[188:191], v158 offset:50176
	ds_read_b128 v[192:195], v158 offset:51200
	ds_read_b128 v[196:199], v158 offset:52224
	ds_read_b128 v[202:205], v158 offset:53248
	ds_read_b128 v[206:209], v158 offset:54272
	ds_read_b128 v[210:213], v158 offset:55296
	ds_read_b128 v[214:217], v158 offset:56320
	global_load_lds_dwordx4 v[218:219], off
	v_lshl_add_u64 v[218:219], v[220:221], 0, s[14:15]
	s_add_i32 m0, s10, 0x2000
	s_add_i32 s10, s58, s47
	global_load_lds_dwordx4 v[218:219], off
	v_lshl_add_u64 v[218:219], v[222:223], 0, s[14:15]
	s_mov_b32 m0, s10
	s_nop 0
	global_load_lds_dwordx4 v[218:219], off
	v_lshl_add_u64 v[218:219], v[224:225], 0, s[14:15]
	s_add_i32 m0, s10, 0x2000
	s_nop 0
	global_load_lds_dwordx4 v[218:219], off
	v_lshl_add_u64 v[218:219], v[226:227], 0, s[14:15]
	s_mov_b32 m0, s53
	s_nop 0
	global_load_lds_dwordx4 v[218:219], off
	v_lshl_add_u64 v[218:219], v[228:229], 0, s[14:15]
	s_mov_b32 m0, s54
	s_nop 0
	global_load_lds_dwordx4 v[218:219], off
	s_waitcnt vmcnt(8)
	s_waitcnt lgkmcnt(0)
	s_barrier
	v_mfma_f32_16x16x32_bf16 v[62:65], v[144:147], v[184:187], v[62:65]
	v_mfma_f32_16x16x32_bf16 v[58:61], v[160:163], v[184:187], v[58:61]
	v_mfma_f32_16x16x32_bf16 v[46:49], v[144:147], v[192:195], v[46:49]
	v_mfma_f32_16x16x32_bf16 v[42:45], v[160:163], v[192:195], v[42:45]
	v_mfma_f32_16x16x32_bf16 v[30:33], v[144:147], v[202:205], v[30:33]
	v_mfma_f32_16x16x32_bf16 v[26:29], v[160:163], v[202:205], v[26:29]
	v_mfma_f32_16x16x32_bf16 v[14:17], v[144:147], v[210:213], v[14:17]
	v_mfma_f32_16x16x32_bf16 v[10:13], v[160:163], v[210:213], v[10:13]
	v_mfma_f32_16x16x32_bf16 v[62:65], v[148:151], v[188:191], v[62:65]
	v_mfma_f32_16x16x32_bf16 v[58:61], v[164:167], v[188:191], v[58:61]
	v_mfma_f32_16x16x32_bf16 v[46:49], v[148:151], v[196:199], v[46:49]
	v_mfma_f32_16x16x32_bf16 v[42:45], v[164:167], v[196:199], v[42:45]
	v_mfma_f32_16x16x32_bf16 v[30:33], v[148:151], v[206:209], v[30:33]
	v_mfma_f32_16x16x32_bf16 v[26:29], v[164:167], v[206:209], v[26:29]
	v_mfma_f32_16x16x32_bf16 v[14:17], v[148:151], v[214:217], v[14:17]
	v_mfma_f32_16x16x32_bf16 v[10:13], v[164:167], v[214:217], v[10:13]
	v_mfma_f32_16x16x32_bf16 v[54:57], v[168:171], v[184:187], v[54:57]
	v_mfma_f32_16x16x32_bf16 v[50:53], v[176:179], v[184:187], v[50:53]
	v_mfma_f32_16x16x32_bf16 v[38:41], v[168:171], v[192:195], v[38:41]
	v_mfma_f32_16x16x32_bf16 v[34:37], v[176:179], v[192:195], v[34:37]
	v_mfma_f32_16x16x32_bf16 v[22:25], v[168:171], v[202:205], v[22:25]
	v_mfma_f32_16x16x32_bf16 v[18:21], v[176:179], v[202:205], v[18:21]
	v_mfma_f32_16x16x32_bf16 v[6:9], v[168:171], v[210:213], v[6:9]
	v_mfma_f32_16x16x32_bf16 v[2:5], v[176:179], v[210:213], v[2:5]
	v_mfma_f32_16x16x32_bf16 v[54:57], v[172:175], v[188:191], v[54:57]
	v_mfma_f32_16x16x32_bf16 v[50:53], v[180:183], v[188:191], v[50:53]
	v_mfma_f32_16x16x32_bf16 v[38:41], v[172:175], v[196:199], v[38:41]
	v_mfma_f32_16x16x32_bf16 v[34:37], v[180:183], v[196:199], v[34:37]
	v_mfma_f32_16x16x32_bf16 v[22:25], v[172:175], v[206:209], v[22:25]
	v_mfma_f32_16x16x32_bf16 v[18:21], v[180:183], v[206:209], v[18:21]
	v_mfma_f32_16x16x32_bf16 v[6:9], v[172:175], v[214:217], v[6:9]
	v_mfma_f32_16x16x32_bf16 v[2:5], v[180:183], v[214:217], v[2:5]
	s_barrier
	s_add_u32 s8, s8, 0x100
	s_addc_u32 s9, s9, 0
	s_add_u32 s34, s34, 0x100
	s_addc_u32 s35, s35, 0
	s_cmp_ge_u32 s36, s52
	s_mov_b32 s10, s36
	s_cbranch_scc0 .LBB0_977
	s_branch .Lg2_after
